# out-proj and ffn-down tile schedulers also resume their scan (all four GEMM phases now O(1) per unit)
# baseline (speedup 1.0000x reference)
.LBB0_99:
	s_mov_b64 s[56:57], s[44:45]
	s_mov_b64 s[58:59], s[46:47]
	s_mov_b32 s30, s34
	s_mov_b32 s51, s22
	s_mov_b32 s70, s50
	s_add_i32 s50, s50, 1
	s_mov_b32 s61, -1
	s_mov_b32 s52, 0
	s_mov_b32 s53, 0
	s_cmp_eq_u32 s70, 0
	s_cbranch_scc1 .Lsr_o8
	s_mov_b32 s61, s70
	s_mov_b32 s53, s100
	s_lshr_b32 s52, s100, 3
	s_mul_i32 s52, s52, s94
.Lsr_o8:
.LBB0_100:
	s_mov_b32 s0, s90
	s_and_b64 vcc, exec, s[40:41]
	s_mov_b64 s[64:65], -1
	s_cbranch_vccnz .LBB0_103
	s_add_i32 s39, s0, s52
	s_mov_b64 s[64:65], 0
	s_cmpk_gt_i32 s39, 0x47f
	s_mov_b64 s[20:21], 0
	s_mov_b32 s62, s63
	s_mov_b32 s60, s37
	s_cbranch_scc1 .LBB0_103
	s_ashr_i32 s20, s39, 31
	s_lshr_b32 s20, s20, 30
	s_add_i32 s20, s39, s20
	s_ashr_i32 s60, s20, 2
	s_and_b32 s20, s20, -4
	s_sub_i32 s62, s39, s20
	s_mov_b64 s[20:21], -1

.LBB0_115:
	s_mov_b32 s100, s53
	s_and_b64 s[20:21], s[54:55], exec
	s_cselect_b32 s20, s45, s57
	s_cselect_b32 s21, s44, s56
	s_cselect_b32 s62, s47, s59
	s_cselect_b32 s63, s46, s58
	s_add_u32 s56, s56, 0x40080
	s_addc_u32 s57, s57, 0
	s_add_u32 s64, s58, 0x100
	v_mov_b32_e32 v0, 0
	s_addc_u32 s65, s59, 0
	s_mov_b32 s70, -2
	v_mov_b32_e32 v1, v0
	v_mov_b32_e32 v2, v0
	v_mov_b32_e32 v3, v0
	v_mov_b32_e32 v4, v0
	v_mov_b32_e32 v5, v0
	v_mov_b32_e32 v6, v0
	v_mov_b32_e32 v7, v0
	v_mov_b32_e32 v8, v0
	v_mov_b32_e32 v9, v0
	v_mov_b32_e32 v10, v0
	v_mov_b32_e32 v11, v0
	v_mov_b32_e32 v12, v0
	v_mov_b32_e32 v13, v0
	v_mov_b32_e32 v14, v0
	v_mov_b32_e32 v15, v0
	v_mov_b32_e32 v16, v0
	v_mov_b32_e32 v17, v0
	v_mov_b32_e32 v18, v0
	v_mov_b32_e32 v19, v0
	v_mov_b32_e32 v20, v0
	v_mov_b32_e32 v21, v0
	v_mov_b32_e32 v22, v0
	v_mov_b32_e32 v23, v0
	v_mov_b32_e32 v24, v0
	v_mov_b32_e32 v25, v0
	v_mov_b32_e32 v26, v0
	v_mov_b32_e32 v27, v0
	v_mov_b32_e32 v28, v0
	v_mov_b32_e32 v29, v0
	v_mov_b32_e32 v30, v0
	v_mov_b32_e32 v31, v0
	v_mov_b32_e32 v64, v0
	v_mov_b32_e32 v65, v0
	v_mov_b32_e32 v66, v0
	v_mov_b32_e32 v67, v0
	v_mov_b32_e32 v68, v0
	v_mov_b32_e32 v69, v0
	v_mov_b32_e32 v70, v0
	v_mov_b32_e32 v71, v0
	v_mov_b32_e32 v72, v0
	v_mov_b32_e32 v73, v0
	v_mov_b32_e32 v74, v0
	v_mov_b32_e32 v75, v0
	v_mov_b32_e32 v76, v0
	v_mov_b32_e32 v77, v0
	v_mov_b32_e32 v78, v0
	v_mov_b32_e32 v79, v0
	v_mov_b32_e32 v80, v0
	v_mov_b32_e32 v81, v0
	v_mov_b32_e32 v82, v0
	v_mov_b32_e32 v83, v0
	v_mov_b32_e32 v84, v0
	v_mov_b32_e32 v85, v0
	v_mov_b32_e32 v86, v0
	v_mov_b32_e32 v87, v0
	v_mov_b32_e32 v88, v0
	v_mov_b32_e32 v89, v0
	v_mov_b32_e32 v90, v0
	v_mov_b32_e32 v91, v0
	v_mov_b32_e32 v92, v0
	v_mov_b32_e32 v93, v0
	v_mov_b32_e32 v94, v0
	v_mov_b32_e32 v95, v0
	v_mov_b32_e32 v32, v0
	v_mov_b32_e32 v33, v0
	v_mov_b32_e32 v34, v0
	v_mov_b32_e32 v35, v0
	v_mov_b32_e32 v36, v0
	v_mov_b32_e32 v37, v0
	v_mov_b32_e32 v38, v0
	v_mov_b32_e32 v39, v0
	v_mov_b32_e32 v40, v0
	v_mov_b32_e32 v41, v0
	v_mov_b32_e32 v42, v0
	v_mov_b32_e32 v43, v0
	v_mov_b32_e32 v44, v0
	v_mov_b32_e32 v45, v0
	v_mov_b32_e32 v46, v0
	v_mov_b32_e32 v47, v0
	v_mov_b32_e32 v48, v0
	v_mov_b32_e32 v49, v0
	v_mov_b32_e32 v50, v0
	v_mov_b32_e32 v51, v0
	v_mov_b32_e32 v52, v0
	v_mov_b32_e32 v53, v0
	v_mov_b32_e32 v54, v0
	v_mov_b32_e32 v55, v0
	v_mov_b32_e32 v56, v0
	v_mov_b32_e32 v57, v0
	v_mov_b32_e32 v58, v0
	v_mov_b32_e32 v59, v0
	v_mov_b32_e32 v60, v0
	v_mov_b32_e32 v61, v0
	v_mov_b32_e32 v62, v0
	v_mov_b32_e32 v63, v0
	v_mov_b32_e32 v96, v0
	v_mov_b32_e32 v97, v0
	v_mov_b32_e32 v98, v0
	v_mov_b32_e32 v99, v0
	v_mov_b32_e32 v100, v0
	v_mov_b32_e32 v101, v0
	v_mov_b32_e32 v102, v0
	v_mov_b32_e32 v103, v0
	v_mov_b32_e32 v104, v0
	v_mov_b32_e32 v105, v0
	v_mov_b32_e32 v106, v0
	v_mov_b32_e32 v107, v0
	v_mov_b32_e32 v108, v0
	v_mov_b32_e32 v109, v0
	v_mov_b32_e32 v110, v0
	v_mov_b32_e32 v111, v0
	v_mov_b32_e32 v112, v0
	v_mov_b32_e32 v113, v0
	v_mov_b32_e32 v114, v0
	v_mov_b32_e32 v115, v0
	v_mov_b32_e32 v116, v0
	v_mov_b32_e32 v117, v0
	v_mov_b32_e32 v118, v0
	v_mov_b32_e32 v119, v0
	v_mov_b32_e32 v120, v0
	v_mov_b32_e32 v121, v0
	v_mov_b32_e32 v122, v0
	v_mov_b32_e32 v123, v0
	v_mov_b32_e32 v124, v0
	v_mov_b32_e32 v125, v0
	v_mov_b32_e32 v126, v0
	v_mov_b32_e32 v127, v0

.LBB0_1234:
	s_mov_b64 s[54:55], s[44:45]
	s_mov_b64 s[56:57], s[46:47]
	s_mov_b32 s50, s30
	s_mov_b32 s69, s22
	s_mov_b32 s48, s68
	s_add_i32 s68, s68, 1
	s_mov_b32 s61, -1
	s_mov_b32 s49, 0
	s_mov_b32 s60, 0
	s_cmp_eq_u32 s48, 0
	s_cbranch_scc1 .Lsr_d8
	s_mov_b32 s61, s48
	s_mov_b32 s60, s100
	s_lshr_b32 s49, s100, 3
	s_mul_i32 s49, s49, s94
.Lsr_d8:
.LBB0_1235:
	s_mov_b32 s39, s90
	s_and_b64 vcc, exec, s[40:41]
	s_mov_b64 s[58:59], -1
	s_cbranch_vccnz .LBB0_1238
	s_add_i32 vcc_lo, s39, s49
	s_mov_b64 s[58:59], 0
	s_cmpk_gt_i32 vcc_lo, 0x47f
	s_mov_b64 s[20:21], 0
	s_mov_b32 s34, s51
	s_mov_b32 s70, s37
	s_cbranch_scc1 .LBB0_1238
	s_ashr_i32 s20, vcc_lo, 31
	s_lshr_b32 s20, s20, 30
	s_add_i32 s20, vcc_lo, s20
	s_ashr_i32 s70, s20, 2
	s_and_b32 s20, s20, -4
	s_sub_i32 s34, vcc_lo, s20
	s_mov_b64 s[20:21], -1

.LBB0_1250:
	s_mov_b32 s100, s60
	s_and_b64 s[20:21], s[52:53], exec
	s_cselect_b32 s20, s45, s55
	s_cselect_b32 s21, s44, s54
	s_cselect_b32 s70, s47, s57
	s_cselect_b32 vcc_lo, s46, s56
	s_add_u32 vcc_hi, s56, 0x100
	v_mov_b32_e32 v0, 0
	s_addc_u32 s48, s57, 0
	s_mov_b32 s49, -2
	v_mov_b32_e32 v1, v0
	v_mov_b32_e32 v2, v0
	v_mov_b32_e32 v3, v0
	v_mov_b32_e32 v4, v0
	v_mov_b32_e32 v5, v0
	v_mov_b32_e32 v6, v0
	v_mov_b32_e32 v7, v0
	v_mov_b32_e32 v8, v0
	v_mov_b32_e32 v9, v0
	v_mov_b32_e32 v10, v0
	v_mov_b32_e32 v11, v0
	v_mov_b32_e32 v12, v0
	v_mov_b32_e32 v13, v0
	v_mov_b32_e32 v14, v0
	v_mov_b32_e32 v15, v0
	v_mov_b32_e32 v16, v0
	v_mov_b32_e32 v17, v0
	v_mov_b32_e32 v18, v0
	v_mov_b32_e32 v19, v0
	v_mov_b32_e32 v20, v0
	v_mov_b32_e32 v21, v0
	v_mov_b32_e32 v22, v0
	v_mov_b32_e32 v23, v0
	v_mov_b32_e32 v24, v0
	v_mov_b32_e32 v25, v0
	v_mov_b32_e32 v26, v0
	v_mov_b32_e32 v27, v0
	v_mov_b32_e32 v28, v0
	v_mov_b32_e32 v29, v0
	v_mov_b32_e32 v30, v0
	v_mov_b32_e32 v31, v0
	v_mov_b32_e32 v64, v0
	v_mov_b32_e32 v65, v0
	v_mov_b32_e32 v66, v0
	v_mov_b32_e32 v67, v0
	v_mov_b32_e32 v68, v0
	v_mov_b32_e32 v69, v0
	v_mov_b32_e32 v70, v0
	v_mov_b32_e32 v71, v0
	v_mov_b32_e32 v72, v0
	v_mov_b32_e32 v73, v0
	v_mov_b32_e32 v74, v0
	v_mov_b32_e32 v75, v0
	v_mov_b32_e32 v76, v0
	v_mov_b32_e32 v77, v0
	v_mov_b32_e32 v78, v0
	v_mov_b32_e32 v79, v0
	v_mov_b32_e32 v80, v0
	v_mov_b32_e32 v81, v0
	v_mov_b32_e32 v82, v0
	v_mov_b32_e32 v83, v0
	v_mov_b32_e32 v84, v0
	v_mov_b32_e32 v85, v0
	v_mov_b32_e32 v86, v0
	v_mov_b32_e32 v87, v0
	v_mov_b32_e32 v88, v0
	v_mov_b32_e32 v89, v0
	v_mov_b32_e32 v90, v0
	v_mov_b32_e32 v91, v0
	v_mov_b32_e32 v92, v0
	v_mov_b32_e32 v93, v0
	v_mov_b32_e32 v94, v0
	v_mov_b32_e32 v95, v0
	v_mov_b32_e32 v32, v0
	v_mov_b32_e32 v33, v0
	v_mov_b32_e32 v34, v0
	v_mov_b32_e32 v35, v0
	v_mov_b32_e32 v36, v0
	v_mov_b32_e32 v37, v0
	v_mov_b32_e32 v38, v0
	v_mov_b32_e32 v39, v0
	v_mov_b32_e32 v40, v0
	v_mov_b32_e32 v41, v0
	v_mov_b32_e32 v42, v0
	v_mov_b32_e32 v43, v0
	v_mov_b32_e32 v44, v0
	v_mov_b32_e32 v45, v0
	v_mov_b32_e32 v46, v0
	v_mov_b32_e32 v47, v0
	v_mov_b32_e32 v48, v0
	v_mov_b32_e32 v49, v0
	v_mov_b32_e32 v50, v0
	v_mov_b32_e32 v51, v0
	v_mov_b32_e32 v52, v0
	v_mov_b32_e32 v53, v0
	v_mov_b32_e32 v54, v0
	v_mov_b32_e32 v55, v0
	v_mov_b32_e32 v56, v0
	v_mov_b32_e32 v57, v0
	v_mov_b32_e32 v58, v0
	v_mov_b32_e32 v59, v0
	v_mov_b32_e32 v60, v0
	v_mov_b32_e32 v61, v0
	v_mov_b32_e32 v62, v0
	v_mov_b32_e32 v63, v0
	v_mov_b32_e32 v96, v0
	v_mov_b32_e32 v97, v0
	v_mov_b32_e32 v98, v0
	v_mov_b32_e32 v99, v0
	v_mov_b32_e32 v100, v0
	v_mov_b32_e32 v101, v0
	v_mov_b32_e32 v102, v0
	v_mov_b32_e32 v103, v0
	v_mov_b32_e32 v104, v0
	v_mov_b32_e32 v105, v0
	v_mov_b32_e32 v106, v0
	v_mov_b32_e32 v107, v0
	v_mov_b32_e32 v108, v0
	v_mov_b32_e32 v109, v0
	v_mov_b32_e32 v110, v0
	v_mov_b32_e32 v111, v0
	v_mov_b32_e32 v112, v0
	v_mov_b32_e32 v113, v0
	v_mov_b32_e32 v114, v0
	v_mov_b32_e32 v115, v0
	v_mov_b32_e32 v116, v0
	v_mov_b32_e32 v117, v0
	v_mov_b32_e32 v118, v0
	v_mov_b32_e32 v119, v0
	v_mov_b32_e32 v120, v0
	v_mov_b32_e32 v121, v0
	v_mov_b32_e32 v122, v0
	v_mov_b32_e32 v123, v0
	v_mov_b32_e32 v124, v0
	v_mov_b32_e32 v125, v0
	v_mov_b32_e32 v126, v0
	v_mov_b32_e32 v127, v0
